# v26: v25 + P5 RMS-norm weights loaded once per phase, 16-lane butterflies by DPP
# speedup vs baseline: 1.0061x; 1.0017x over previous
; #define LAS __attribute__((address_space(3)))
; DI unsigned pk2(float lo, float hi) { f32x2 v = {lo, hi}; bfv2 b = __builtin_convertvector(v, bfv2); return __builtin_bit_cast(unsigned, b); }
; DI bf16_t f2bf(float x) { return (bf16_t)(pk2(x, 0.f) & 0xffffu); }
; #define MFMA16(a, b, c) __builtin_amdgcn_mfma_f32_16x16x32_bf16((a), (b), (c), 0, 0, 0)
; template <bool OUT> DI void hgrn_item(LAS unsigned char* lds, bf16_t* proj, float* hst, float* hdv, const float* normw, int item, bool dry) {
;     ...
;                 for (int r = 0; r < 4; ++r) { const int tt = 16 * ti + 4 * rq + r, ss = 16 * sj + e16; Ab[tt * TP + ss] = (sj <= ti && ss <= tt) ? f2bf(a[r]) : (bf16_t)0; }
;             }
; #pragma unroll
;             for (int ti = 0; ti < 4; ++ti) { o[ti] = (f32x4){0.f, 0.f, 0.f, 0.f};
; #pragma unroll
;                 for (int ks = 0; ks < 4; ++ks) { const LAS bf16_t* qp = Qt + (16 * ti + e16) * QP + 32 * ks + 4 * rq; const u32x2 q0 = *(const LAS u32x2*)qp, q1 = *(const LAS u32x2*)(qp + 16);
;                     u32x4 qa = {q0.x, q0.y, q1.x, q1.y};
;                     u32x4 sb; sb.x = pk2(st[2 * ks][0], st[2 * ks][1]); sb.y = pk2(st[2 * ks][2], st[2 * ks][3]); sb.z = pk2(st[2 * ks + 1][0], st[2 * ks + 1][1]); sb.w = pk2(st[2 * ks + 1][2], st[2 * ks + 1][3]);
;                     o[ti] = MFMA16(__builtin_bit_cast(bf16x8, qa), __builtin_bit_cast(bf16x8, sb), o[ti]); } }
;         }
; #pragma unroll
;         for (int dt = 0; dt < 8; ++dt) {
; #pragma unroll
;             for (int ks = 0; ks < 2; ++ks) { const bf16x8 ka = *(const LAS bf16x8*)(KtT + (16 * dt + e16) * TP + 32 * ks + 8 * rq); st[dt] = MFMA16(ka, vfr[ks], st[dt]); }
;             const f32x4 dv = *(const LAS f32x4*)(Dv + 16 * dt + 4 * rq);
;             st[dt] *= dv;
;         }
.LBB0_1170:
	v_or_b32_e32 v56, s14, v104
	v_cmp_gt_u32_e32 vcc, v120, v56
	s_or_b64 s[36:37], s[20:21], vcc
	s_nop 3
	v_cvt_pk_bf16_f32 v50, v50, s0
	v_cndmask_b32_e64 v50, v50, 0, s[36:37]
	v_mad_u64_u32 v[54:55], s[36:37], v56, s39, v[92:93]
	ds_write_b16 v54, v50
	v_or_b32_e32 v50, 1, v56
	v_cmp_gt_u32_e32 vcc, v120, v50
	s_or_b64 s[36:37], s[20:21], vcc
	v_cvt_pk_bf16_f32 v50, v51, s0
	v_cndmask_b32_e64 v50, v50, 0, s[36:37]
	ds_write_b16 v54, v50 offset:144
	v_or_b32_e32 v50, 2, v56
	v_cmp_gt_u32_e32 vcc, v120, v50
	s_or_b64 s[36:37], s[20:21], vcc
	v_cvt_pk_bf16_f32 v50, v52, s0
	v_cndmask_b32_e64 v50, v50, 0, s[36:37]
	ds_write_b16 v54, v50 offset:288
	v_or_b32_e32 v50, 3, v56
	v_cmp_gt_u32_e32 vcc, v120, v50
	s_or_b64 s[36:37], s[20:21], vcc
	v_cvt_pk_bf16_f32 v50, v53, s0
	v_cndmask_b32_e64 v50, v50, 0, s[36:37]
	ds_write_b16 v54, v50 offset:432
	ds_read2_b64 v[50:53], v115 offset1:4
	ds_read2_b64 v[54:57], v115 offset0:8 offset1:12
	s_waitcnt vmcnt(7)
	v_cvt_pk_bf16_f32 v66, v6, v7
	v_cvt_pk_bf16_f32 v67, v8, v9
	s_waitcnt vmcnt(6)
	v_cvt_pk_bf16_f32 v68, v10, v11
	v_cvt_pk_bf16_f32 v69, v12, v13
	s_waitcnt vmcnt(5)
	v_cvt_pk_bf16_f32 v70, v2, v3
	v_cvt_pk_bf16_f32 v71, v4, v5
	s_waitcnt lgkmcnt(1)
	v_mfma_f32_16x16x32_bf16 v[50:53], v[50:53], v[66:69], 0
	s_waitcnt vmcnt(4)
	v_cvt_pk_bf16_f32 v72, v18, v19
	v_cvt_pk_bf16_f32 v73, v20, v21
	s_waitcnt vmcnt(3)
	v_cvt_pk_bf16_f32 v100, v14, v15
	v_cvt_pk_bf16_f32 v101, v16, v17
	s_waitcnt lgkmcnt(0)
	v_mfma_f32_16x16x32_bf16 v[50:53], v[54:57], v[70:73], v[50:53]
	ds_read2_b64 v[54:57], v115 offset0:16 offset1:20
	s_waitcnt vmcnt(2)
	v_cvt_pk_bf16_f32 v102, v26, v27
	v_cvt_pk_bf16_f32 v103, v28, v29
	s_waitcnt vmcnt(1)
	v_cvt_pk_bf16_f32 v144, v22, v23
	v_cvt_pk_bf16_f32 v145, v24, v25
	s_waitcnt lgkmcnt(0)
	v_mfma_f32_16x16x32_bf16 v[50:53], v[54:57], v[100:103], v[50:53]
	ds_read2_b64 v[54:57], v115 offset0:24 offset1:28
	s_waitcnt vmcnt(0)
	v_cvt_pk_bf16_f32 v146, v30, v31
	v_cvt_pk_bf16_f32 v147, v32, v33
	v_add_u32_e32 v62, 0x1000, v115
	ds_read2_b64 v[58:61], v62 offset0:40 offset1:44
	s_waitcnt lgkmcnt(1)
	v_mfma_f32_16x16x32_bf16 v[54:57], v[54:57], v[144:147], v[50:53]
	s_nop 2
	ds_read2_b64 v[50:53], v62 offset0:32 offset1:36
	v_add_u32_e32 v143, 0x2000, v115
	s_waitcnt lgkmcnt(0)
	v_mfma_f32_16x16x32_bf16 v[50:53], v[50:53], v[66:69], 0
	v_mfma_f32_16x16x32_bf16 v[50:53], v[58:61], v[70:73], v[50:53]
	ds_read2_b64 v[58:61], v62 offset0:48 offset1:52
	s_waitcnt lgkmcnt(0)
	v_mfma_f32_16x16x32_bf16 v[50:53], v[58:61], v[100:103], v[50:53]
	ds_read2_b64 v[58:61], v62 offset0:56 offset1:60
	ds_read2_b64 v[62:65], v143 offset0:72 offset1:76
	s_waitcnt lgkmcnt(1)
	v_mfma_f32_16x16x32_bf16 v[58:61], v[58:61], v[144:147], v[50:53]
	s_nop 3
	ds_read2_b64 v[50:53], v143 offset0:64 offset1:68
	s_waitcnt lgkmcnt(0)
	v_mfma_f32_16x16x32_bf16 v[50:53], v[50:53], v[66:69], 0
	v_mfma_f32_16x16x32_bf16 v[50:53], v[62:65], v[70:73], v[50:53]
	ds_read2_b64 v[62:65], v143 offset0:80 offset1:84
	s_waitcnt lgkmcnt(0)
	v_mfma_f32_16x16x32_bf16 v[50:53], v[62:65], v[100:103], v[50:53]
	ds_read2_b64 v[62:65], v143 offset0:88 offset1:92
	v_add_u32_e32 v143, 0x3000, v115
	s_waitcnt lgkmcnt(0)
	v_mfma_f32_16x16x32_bf16 v[62:65], v[62:65], v[144:147], v[50:53]
	s_nop 3
	ds_read2_b64 v[50:53], v143 offset0:96 offset1:100
	s_waitcnt lgkmcnt(0)
	v_mfma_f32_16x16x32_bf16 v[50:53], v[50:53], v[66:69], 0
	ds_read2_b64 v[66:69], v143 offset0:104 offset1:108
	s_waitcnt lgkmcnt(0)
	v_mfma_f32_16x16x32_bf16 v[50:53], v[66:69], v[70:73], v[50:53]
	ds_read2_b64 v[66:69], v143 offset0:112 offset1:116
	s_waitcnt lgkmcnt(0)
	v_mfma_f32_16x16x32_bf16 v[50:53], v[66:69], v[100:103], v[50:53]
	ds_read2_b64 v[66:69], v143 offset0:120 offset1:124
	v_lshl_add_u64 v[102:103], v[98:99], 0, s[34:35]
	v_lshl_add_u64 v[100:101], v[96:97], 0, s[34:35]
	s_waitcnt lgkmcnt(0)
	v_mfma_f32_16x16x32_bf16 v[70:73], v[66:69], v[144:147], v[50:53]
	v_add_u32_e32 v66, v93, v108
	s_nop 1
	ds_read_b128 v[50:53], v66 offset:34816
	v_add_u32_e32 v67, 0x13c00, v93
	s_waitcnt lgkmcnt(0)
	v_mfma_f32_16x16x32_bf16 v[6:9], v[50:53], v[46:49], v[6:9]
	ds_read_b128 v[50:53], v66 offset:34880
	s_add_u32 s34, s34, 0xc8000
	s_addc_u32 s35, s35, 0
	s_waitcnt lgkmcnt(0)
	v_mfma_f32_16x16x32_bf16 v[6:9], v[50:53], v[42:45], v[6:9]
	ds_read_b128 v[50:53], v67
	s_cmp_lg_u32 s34, 0x320000
	s_waitcnt lgkmcnt(0)
	s_nop 4
	v_pk_mul_f32 v[8:9], v[8:9], v[52:53]
	v_pk_mul_f32 v[6:7], v[6:7], v[50:51]
	ds_read_b128 v[50:53], v66 offset:37120
	s_waitcnt lgkmcnt(0)
	v_mfma_f32_16x16x32_bf16 v[10:13], v[50:53], v[46:49], v[10:13]
	ds_read_b128 v[50:53], v66 offset:37184
	s_waitcnt lgkmcnt(0)
	v_mfma_f32_16x16x32_bf16 v[10:13], v[50:53], v[42:45], v[10:13]
	ds_read_b128 v[50:53], v67 offset:64
	s_waitcnt lgkmcnt(0)
	s_nop 5
	v_pk_mul_f32 v[12:13], v[12:13], v[52:53]
	v_pk_mul_f32 v[10:11], v[10:11], v[50:51]
	ds_read_b128 v[50:53], v66 offset:39424
	s_waitcnt lgkmcnt(0)
	v_mfma_f32_16x16x32_bf16 v[2:5], v[50:53], v[46:49], v[2:5]
	ds_read_b128 v[50:53], v66 offset:39488
	s_waitcnt lgkmcnt(0)
	v_mfma_f32_16x16x32_bf16 v[2:5], v[50:53], v[42:45], v[2:5]
	ds_read_b128 v[50:53], v67 offset:128
	s_waitcnt lgkmcnt(0)
	s_nop 5
	v_pk_mul_f32 v[4:5], v[4:5], v[52:53]
	v_pk_mul_f32 v[2:3], v[2:3], v[50:51]
	ds_read_b128 v[50:53], v66 offset:41728
	s_waitcnt lgkmcnt(0)
	v_mfma_f32_16x16x32_bf16 v[18:21], v[50:53], v[46:49], v[18:21]
	ds_read_b128 v[50:53], v66 offset:41792
	s_waitcnt lgkmcnt(0)
	v_mfma_f32_16x16x32_bf16 v[18:21], v[50:53], v[42:45], v[18:21]
	ds_read_b128 v[50:53], v67 offset:192
	s_waitcnt lgkmcnt(0)
; #define LAS __attribute__((address_space(3)))
; #define MFMA16(a, b, c) __builtin_amdgcn_mfma_f32_16x16x32_bf16((a), (b), (c), 0, 0, 0)
; template <bool OUT> DI void hgrn_item(LAS unsigned char* lds, bf16_t* proj, float* hst, float* hdv, const float* normw, int item, bool dry) {
;     ...
; #pragma unroll
;         for (int dt = 0; dt < 8; ++dt) {
; #pragma unroll
;             for (int ks = 0; ks < 2; ++ks) { const bf16x8 ka = *(const LAS bf16x8*)(KtT + (16 * dt + e16) * TP + 32 * ks + 8 * rq); st[dt] = MFMA16(ka, vfr[ks], st[dt]); }
;             const f32x4 dv = *(const LAS f32x4*)(Dv + 16 * dt + 4 * rq);
;             st[dt] *= dv;
;         }
;         u32x4 gate8[2];
;         if (OUT) {
; #pragma unroll
;             for (int j = 0; j < 2; ++j) { const int cch = tid + 512 * j; gate8[j] = *(const u32x4*)(proj + (row0 + (cch >> 4)) * NPJ + C_HG + h * 128 + 8 * (cch & 15)); }
;         }
;         __syncthreads();
;         if (OUT) {
; #pragma unroll
;             for (int ti = 0; ti < 4; ++ti)
; #pragma unroll
;                 for (int ks = 0; ks < 2; ++ks) if (2 * ks <= ti) { const bf16x8 aa = *(const LAS bf16x8*)(Ab + (16 * ti + e16) * TP + 32 * ks + 8 * rq); o[ti] = MFMA16(aa, vfr[ks], o[ti]); }
;             LAS float* Ob = (LAS float*)(lds + HOB_OFF);
; #pragma unroll
;             for (int ti = 0; ti < 4; ++ti)
; #pragma unroll
;                 for (int r = 0; r < 4; ++r) Ob[(16 * ti + 4 * rq + r) * OBP + w * 16 + e16] = o[ti][r];
	s_nop 5
	v_pk_mul_f32 v[20:21], v[20:21], v[52:53]
	v_pk_mul_f32 v[18:19], v[18:19], v[50:51]
	ds_read_b128 v[50:53], v66 offset:44032
	s_waitcnt lgkmcnt(0)
	v_mfma_f32_16x16x32_bf16 v[14:17], v[50:53], v[46:49], v[14:17]
	ds_read_b128 v[50:53], v66 offset:44096
	s_waitcnt lgkmcnt(0)
	v_mfma_f32_16x16x32_bf16 v[14:17], v[50:53], v[42:45], v[14:17]
	ds_read_b128 v[50:53], v67 offset:256
	s_waitcnt lgkmcnt(0)
	s_nop 5
	v_pk_mul_f32 v[16:17], v[16:17], v[52:53]
	v_pk_mul_f32 v[14:15], v[14:15], v[50:51]
	ds_read_b128 v[50:53], v66 offset:46336
	s_waitcnt lgkmcnt(0)
	v_mfma_f32_16x16x32_bf16 v[26:29], v[50:53], v[46:49], v[26:29]
	ds_read_b128 v[50:53], v66 offset:46400
	s_waitcnt lgkmcnt(0)
	v_mfma_f32_16x16x32_bf16 v[26:29], v[50:53], v[42:45], v[26:29]
	ds_read_b128 v[50:53], v67 offset:320
	s_waitcnt lgkmcnt(0)
	s_nop 5
	v_pk_mul_f32 v[28:29], v[28:29], v[52:53]
	v_pk_mul_f32 v[26:27], v[26:27], v[50:51]
	ds_read_b128 v[50:53], v66 offset:48640
	s_waitcnt lgkmcnt(0)
	v_mfma_f32_16x16x32_bf16 v[22:25], v[50:53], v[46:49], v[22:25]
	ds_read_b128 v[50:53], v66 offset:48704
	s_waitcnt lgkmcnt(0)
	v_mfma_f32_16x16x32_bf16 v[22:25], v[50:53], v[42:45], v[22:25]
	ds_read_b128 v[50:53], v67 offset:384
	s_waitcnt lgkmcnt(0)
	s_nop 5
	v_pk_mul_f32 v[24:25], v[24:25], v[52:53]
	v_pk_mul_f32 v[22:23], v[22:23], v[50:51]
	ds_read_b128 v[50:53], v66 offset:50944
	s_waitcnt lgkmcnt(0)
	v_mfma_f32_16x16x32_bf16 v[30:33], v[50:53], v[46:49], v[30:33]
	ds_read_b128 v[50:53], v66 offset:51008
	s_waitcnt lgkmcnt(0)
	v_mfma_f32_16x16x32_bf16 v[30:33], v[50:53], v[42:45], v[30:33]
	ds_read_b128 v[50:53], v67 offset:448
	s_waitcnt lgkmcnt(0)
	s_nop 5
	v_pk_mul_f32 v[30:31], v[30:31], v[50:51]
	v_add_co_u32_e32 v50, vcc, s47, v102
	v_pk_mul_f32 v[32:33], v[32:33], v[52:53]
	s_nop 0
	v_addc_co_u32_e32 v51, vcc, 0, v103, vcc
	global_load_dwordx4 v[66:69], v[50:51], off offset:512
	v_add_co_u32_e32 v50, vcc, s47, v100
	s_nop 1
	v_addc_co_u32_e32 v51, vcc, 0, v101, vcc
	global_load_dwordx4 v[50:53], v[50:51], off offset:512
	s_barrier
	ds_read_b128 v[144:147], v116
	s_waitcnt lgkmcnt(0)
	v_mfma_f32_16x16x32_bf16 v[54:57], v[144:147], v[46:49], v[54:57]
	ds_read_b128 v[144:147], v116 offset:2304
	s_waitcnt lgkmcnt(0)
	v_mfma_f32_16x16x32_bf16 v[58:61], v[144:147], v[46:49], v[58:61]
	ds_read_b128 v[144:147], v116 offset:4608
	s_waitcnt lgkmcnt(0)
	v_mfma_f32_16x16x32_bf16 v[62:65], v[144:147], v[46:49], v[62:65]
	ds_read_b128 v[144:147], v116 offset:4672
	s_waitcnt lgkmcnt(0)
	v_mfma_f32_16x16x32_bf16 v[62:65], v[144:147], v[42:45], v[62:65]
	ds_read_b128 v[144:147], v116 offset:6912
	s_waitcnt lgkmcnt(0)
	v_mfma_f32_16x16x32_bf16 v[46:49], v[144:147], v[46:49], v[70:73]
	s_nop 2
	ds_read_b128 v[70:73], v116 offset:6976
	ds_write2_b32 v125, v54, v55 offset1:132
	s_waitcnt lgkmcnt(1)
	v_mfma_f32_16x16x32_bf16 v[42:45], v[70:73], v[42:45], v[46:49]
	s_nop 2
	v_add_u32_e32 v46, 0x400, v125
	ds_write2_b32 v46, v56, v57 offset0:8 offset1:140
	v_add_u32_e32 v46, 0x2000, v125
	ds_write2_b32 v46, v58, v59 offset0:64 offset1:196
	v_add_u32_e32 v46, 0x2400, v125
	ds_write2_b32 v46, v60, v61 offset0:72 offset1:204
	v_add_u32_e32 v46, 0x4200, v125
	ds_write2_b32 v46, v62, v63 offset1:132
	v_add_u32_e32 v46, 0x4600, v125
	ds_write2_b32 v46, v64, v65 offset0:8 offset1:140
	v_add_u32_e32 v46, 0x6200, v125
	ds_write2_b32 v46, v42, v43 offset0:64 offset1:196
	v_add_u32_e32 v42, 0x6600, v125
	ds_write2_b32 v42, v44, v45 offset0:72 offset1:204
	s_waitcnt lgkmcnt(0)
	s_barrier
; #define LAS __attribute__((address_space(3)))
; DI float bflo(unsigned w) { return __uint_as_float(w << 16); }
; DI float bfhi(unsigned w) { return __uint_as_float(w & 0xffff0000u); }
; DI u32x4 pack8(f32x4 a, f32x4 b) { u32x4 w; w.x = pk2(a[0], a[1]); w.y = pk2(a[2], a[3]); w.z = pk2(b[0], b[1]); w.w = pk2(b[2], b[3]); return w; }
; template <bool OUT> DI void hgrn_item(LAS unsigned char* lds, bf16_t* proj, float* hst, float* hdv, const float* normw, int item, bool dry) {
;     ...
;     HG_LOAD(0);
; #pragma unroll 1
;     for (int sc = 0; sc < 4; ++sc) {
;         const size_t row0 = (size_t)b * 4096 + c * 256 + sc * 64;
;         float gl[16], qv[16];
; #pragma unroll
;         for (int i = 0; i < 8; ++i) { gl[2 * i] = bflo(rg[i]); gl[2 * i + 1] = bfhi(rg[i]); if (OUT) { qv[2 * i] = bflo(rqv[i]); qv[2 * i + 1] = bfhi(rqv[i]); } }
;         *(LAS u32x4*)(VT + d * TP + tq * 16) = (u32x4){rvv[0], rvv[1], rvv[2], rvv[3]};
;         *(LAS u32x4*)(VT + d * TP + tq * 16 + 8) = (u32x4){rvv[4], rvv[5], rvv[6], rvv[7]};
;     ...
; #pragma unroll
;             for (int j = 0; j < 2; ++j) { const int cch = tid + 512 * j, tt = cch >> 4, e0 = 8 * (cch & 15);
;                 const f32x4 a0 = *(const LAS f32x4*)(Ob + tt * OBP + e0), a1 = *(const LAS f32x4*)(Ob + tt * OBP + e0 + 4);
;                 float q = (a0[0] * a0[0] + a0[1] * a0[1]) + (a0[2] * a0[2] + a0[3] * a0[3]) + (a1[0] * a1[0] + a1[1] * a1[1]) + (a1[2] * a1[2] + a1[3] * a1[3]);
;                 q += __shfl_xor(q, 1); q += __shfl_xor(q, 2); q += __shfl_xor(q, 4); q += __shfl_xor(q, 8);
;                 const float rs = __builtin_amdgcn_rsqf(q * (1.0f / 128.0f) + 1e-6f);
;                 const f32x4 n0 = *(const f32x4*)(normw + e0), n1 = *(const f32x4*)(normw + e0 + 4); const u32x4 g = gate8[j];
;                 f32x4 y0, y1;
;                 y0[0] = a0[0] * rs * n0[0] * bflo(g.x); y0[1] = a0[1] * rs * n0[1] * bfhi(g.x); y0[2] = a0[2] * rs * n0[2] * bflo(g.y); y0[3] = a0[3] * rs * n0[3] * bfhi(g.y);
;                 y1[0] = a1[0] * rs * n1[0] * bflo(g.z); y1[1] = a1[1] * rs * n1[1] * bfhi(g.z); y1[2] = a1[2] * rs * n1[2] * bflo(g.w); y1[3] = a1[3] * rs * n1[3] * bfhi(g.w);
;                 if (!dry) *(u32x4*)(proj + (row0 + tt) * NPJ + C_HQ + h * 128 + e0) = pack8(y0, y1); }
	ds_read_b128 v[42:45], v117
	ds_read_b128 v[46:49], v117 offset:16
	s_waitcnt vmcnt(1)
	v_lshlrev_b32_e32 v64, 16, v68
	v_and_b32_e32 v65, 0xffff0000, v68
	s_waitcnt lgkmcnt(1)
	v_pk_mul_f32 v[54:55], v[44:45], v[44:45]
	v_pk_mul_f32 v[56:57], v[42:43], v[42:43]
	s_nop 0
	v_pk_mov_b32 v[58:59], v[56:57], v[54:55] op_sel:[1,0]
	v_mov_b32_e32 v57, v55
	v_pk_add_f32 v[54:55], v[58:59], v[56:57]
	s_waitcnt lgkmcnt(0)
	v_pk_mul_f32 v[56:57], v[48:49], v[48:49]
	v_pk_mul_f32 v[58:59], v[46:47], v[46:47]
	v_mov_b32_e32 v60, v56
	v_mov_b32_e32 v61, v58
	v_mov_b32_e32 v58, v57
	v_pk_add_f32 v[56:57], v[60:61], v[58:59]
	v_add_f32_e32 v54, v54, v55
	v_add_f32_e32 v54, v54, v57
	v_add_f32_e32 v54, v56, v54
	s_nop 1
	v_add_f32_dpp v54, v54, v54 quad_perm:[1,0,3,2] row_mask:0xf bank_mask:0xf
	s_nop 1
	v_add_f32_dpp v54, v54, v54 quad_perm:[2,3,0,1] row_mask:0xf bank_mask:0xf
	s_nop 1
	v_add_f32_dpp v62, v54, v54 row_half_mirror row_mask:0xf bank_mask:0xf
	s_nop 1
	v_add_f32_dpp v62, v62, v62 row_mirror row_mask:0xf bank_mask:0xf
	v_fmamk_f32 v62, v62, 0x3c000000, v118
	v_rsq_f32_e32 v62, v62
	s_nop 0
	v_pk_mul_f32 v[46:47], v[46:47], v[62:63] op_sel_hi:[1,0]
	v_pk_mul_f32 v[48:49], v[48:49], v[62:63] op_sel_hi:[1,0]
	v_pk_mul_f32 v[42:43], v[42:43], v[62:63] op_sel_hi:[1,0]
	v_pk_mul_f32 v[44:45], v[44:45], v[62:63] op_sel_hi:[1,0]
	s_waitcnt vmcnt(0)
	v_pk_mul_f32 v[42:43], v[232:233], v[42:43]
	v_pk_mul_f32 v[46:47], v[236:237], v[46:47]
	v_lshlrev_b32_e32 v58, 16, v69
	v_and_b32_e32 v59, 0xffff0000, v69
	v_pk_mul_f32 v[48:49], v[238:239], v[48:49]
	v_lshlrev_b32_e32 v54, 16, v67
	v_pk_mul_f32 v[48:49], v[48:49], v[58:59]
	v_lshlrev_b32_e32 v58, 16, v66
	v_and_b32_e32 v59, 0xffff0000, v66
	v_and_b32_e32 v55, 0xffff0000, v67
	v_pk_mul_f32 v[44:45], v[234:235], v[44:45]
	v_pk_mul_f32 v[46:47], v[46:47], v[64:65]
	v_pk_mul_f32 v[42:43], v[42:43], v[58:59]
	v_pk_mul_f32 v[44:45], v[44:45], v[54:55]
	v_cvt_pk_bf16_f32 v42, v42, v43
	v_cvt_pk_bf16_f32 v43, v44, v45
	v_cvt_pk_bf16_f32 v44, v46, v47
	v_cvt_pk_bf16_f32 v45, v48, v49
	global_store_dwordx4 v[102:103], v[42:45], off offset:1536
	ds_read_b128 v[42:45], v119
	ds_read_b128 v[46:49], v119 offset:16
	v_lshlrev_b32_e32 v64, 16, v52
	v_and_b32_e32 v65, 0xffff0000, v52
	v_lshlrev_b32_e32 v52, 16, v53
	s_waitcnt lgkmcnt(1)
	v_pk_mul_f32 v[54:55], v[44:45], v[44:45]
	v_pk_mul_f32 v[56:57], v[42:43], v[42:43]
	v_and_b32_e32 v53, 0xffff0000, v53
	v_pk_mov_b32 v[58:59], v[56:57], v[54:55] op_sel:[1,0]
	v_mov_b32_e32 v57, v55
	v_pk_add_f32 v[54:55], v[58:59], v[56:57]
	s_waitcnt lgkmcnt(0)
	v_pk_mul_f32 v[56:57], v[48:49], v[48:49]
	v_pk_mul_f32 v[58:59], v[46:47], v[46:47]
	v_mov_b32_e32 v60, v56
	v_mov_b32_e32 v61, v58
	v_mov_b32_e32 v58, v57
	v_pk_add_f32 v[56:57], v[60:61], v[58:59]
	v_add_f32_e32 v54, v54, v55
	v_add_f32_e32 v54, v54, v57
	v_add_f32_e32 v54, v56, v54
	s_nop 1
	v_add_f32_dpp v54, v54, v54 quad_perm:[1,0,3,2] row_mask:0xf bank_mask:0xf
	s_nop 1
	v_add_f32_dpp v54, v54, v54 quad_perm:[2,3,0,1] row_mask:0xf bank_mask:0xf
	s_nop 1
	v_add_f32_dpp v62, v54, v54 row_half_mirror row_mask:0xf bank_mask:0xf
	s_nop 1
	v_add_f32_dpp v62, v62, v62 row_mirror row_mask:0xf bank_mask:0xf
	v_fmamk_f32 v62, v62, 0x3c000000, v118
	v_rsq_f32_e32 v62, v62
	s_nop 0
	v_pk_mul_f32 v[48:49], v[48:49], v[62:63] op_sel_hi:[1,0]
	v_pk_mul_f32 v[46:47], v[46:47], v[62:63] op_sel_hi:[1,0]
	v_pk_mul_f32 v[42:43], v[42:43], v[62:63] op_sel_hi:[1,0]
	v_pk_mul_f32 v[44:45], v[44:45], v[62:63] op_sel_hi:[1,0]
	v_pk_mul_f32 v[42:43], v[232:233], v[42:43]
	v_pk_mul_f32 v[48:49], v[238:239], v[48:49]
	v_pk_mul_f32 v[46:47], v[236:237], v[46:47]
	v_pk_mul_f32 v[48:49], v[48:49], v[52:53]
	v_lshlrev_b32_e32 v52, 16, v50
	v_and_b32_e32 v53, 0xffff0000, v50
	v_lshlrev_b32_e32 v50, 16, v51
	v_and_b32_e32 v51, 0xffff0000, v51
	v_pk_mul_f32 v[44:45], v[234:235], v[44:45]
	v_pk_mul_f32 v[46:47], v[46:47], v[64:65]
	v_pk_mul_f32 v[42:43], v[42:43], v[52:53]
	v_pk_mul_f32 v[44:45], v[44:45], v[50:51]
	v_cvt_pk_bf16_f32 v42, v42, v43
	v_cvt_pk_bf16_f32 v43, v44, v45
	v_cvt_pk_bf16_f32 v44, v46, v47
	v_cvt_pk_bf16_f32 v45, v48, v49
	global_store_dwordx4 v[100:101], v[42:45], off offset:1536
	s_waitcnt vmcnt(1)
	v_lshl_or_b32 v129, v185, 16, v184
	v_lshl_or_b32 v127, v190, 16, v191
	v_lshl_or_b32 v131, v192, 16, v188
	v_lshl_or_b32 v128, v194, 16, v189
	v_lshl_or_b32 v133, v196, 16, v195
	v_lshl_or_b32 v135, v203, 16, v202
	v_lshl_or_b32 v134, v214, 16, v215
	v_lshl_or_b32 v34, v187, 16, v186
	v_lshl_or_b32 v35, v199, 16, v193
	v_lshl_or_b32 v36, v200, 16, v197
	v_lshl_or_b32 v130, v198, 16, v201
	v_lshl_or_b32 v37, v205, 16, v204
	v_lshl_or_b32 v132, v206, 16, v207
	v_lshl_or_b32 v137, v209, 16, v208
	v_lshl_or_b32 v38, v211, 16, v210
	v_lshl_or_b32 v139, v216, 16, v212
	v_lshl_or_b32 v136, v218, 16, v213
	v_lshl_or_b32 v141, v220, 16, v219
	v_lshl_or_b32 v39, v223, 16, v217
	v_lshl_or_b32 v40, v224, 16, v221
	v_lshl_or_b32 v138, v222, 16, v225
	v_lshl_or_b32 v142, v227, 16, v226
	v_lshl_or_b32 v41, v229, 16, v228
	v_lshl_or_b32 v140, v230, 16, v231
	v_mov_b32_e32 v46, v127
	v_mov_b32_e32 v47, v128
	v_mov_b32_e32 v49, v130
	v_mov_b32_e32 v51, v132
	v_mov_b32_e32 v52, v134
	v_mov_b32_e32 v53, v136
	v_mov_b32_e32 v54, v138
	v_mov_b32_e32 v48, v140
	v_mov_b32_e32 v42, v129
	v_mov_b32_e32 v43, v131
	v_mov_b32_e32 v44, v133
	v_mov_b32_e32 v45, v135
	v_mov_b32_e32 v50, v137
	v_mov_b32_e32 v55, v139
	v_mov_b32_e32 v56, v141
	v_mov_b32_e32 v57, v142
	s_cbranch_scc0 .LBB0_1168
